# P9 EpiZg main epilogue software-pipelined by one row group (register banks, counted vmcnt(2), stores stay in flight) + cache-line touches; VGPR budget 256
# speedup vs baseline: 1.0044x; 1.0004x over previous
.LBB0_2919:
	v_lshl_add_u32 v154, s4, 8, v163
	v_ashrrev_i32_e32 v155, 31, v154
	v_lshlrev_b64 v[156:157], 6, v[154:155]
	v_lshl_add_u64 v[156:157], v[138:139], 0, v[156:157]
	global_load_dwordx4 v[172:175], v[156:157], off
	v_lshl_or_b32 v150, s5, 7, v165
	v_ashrrev_i32_e32 v151, 31, v150
	s_lshl_b32 s4, s5, 3
	v_lshlrev_b64 v[150:151], 1, v[150:151]
	s_ashr_i32 s5, s4, 31
	v_lshl_add_u64 v[152:153], s[14:15], 0, v[150:151]
	s_lshl_b64 s[4:5], s[4:5], 2
	v_lshlrev_b64 v[158:159], 11, v[154:155]
	v_lshl_add_u64 v[196:197], v[152:153], 0, v[158:159]
	s_add_u32 s44, s56, s4
	global_load_dwordx4 v[176:179], v[196:197], off
	s_addc_u32 s45, s57, s5
	v_lshlrev_b64 v[156:157], 8, v[154:155]
	v_lshl_add_u64 v[156:157], s[44:45], 0, v[156:157]
	global_load_dwordx4 v[180:183], v[156:157], off
	global_load_dwordx4 v[184:187], v[156:157], off offset:16
	global_load_dwordx4 v[188:191], v[140:141], off
	global_load_dwordx4 v[192:195], v[140:141], off offset:16
	v_lshlrev_b64 v[202:203], 6, v[154:155]
	v_lshl_add_u64 v[202:203], v[138:139], 0, v[202:203]
	v_mov_b64_e32 v[236:237], v[156:157]
	v_mov_b64_e32 v[200:201], v[196:197]
	s_mov_b32 s47, 0
	s_mov_b32 s46, 0x2000
	v_lshl_add_u64 v[254:255], v[202:203], 0, s[46:47]
	global_load_dword v239, v[202:203], off offset:1024
	s_mov_b32 s46, 0x1000
	v_lshl_add_u64 v[204:205], v[236:237], 0, s[46:47]
	global_load_dword v239, v[204:205], off
	s_mov_b32 s46, 0x8000
	v_lshl_add_u64 v[206:207], v[200:201], 0, s[46:47]
	global_load_dword v239, v[206:207], off
	global_load_dword v239, v[202:203], off offset:2048
	s_mov_b32 s46, 0x2000
	v_lshl_add_u64 v[208:209], v[236:237], 0, s[46:47]
	global_load_dword v239, v[208:209], off
	s_mov_b32 s46, 0x10000
	v_lshl_add_u64 v[210:211], v[200:201], 0, s[46:47]
	global_load_dword v239, v[210:211], off
	global_load_dword v239, v[202:203], off offset:3072
	s_mov_b32 s46, 0x3000
	v_lshl_add_u64 v[212:213], v[236:237], 0, s[46:47]
	global_load_dword v239, v[212:213], off
	s_mov_b32 s46, 0x18000
	v_lshl_add_u64 v[214:215], v[200:201], 0, s[46:47]
	global_load_dword v239, v[214:215], off
	global_load_dword v239, v[254:255], off offset:0
	s_mov_b32 s46, 0x8000
	v_lshl_add_u64 v[216:217], v[236:237], 0, s[46:47]
	global_load_dword v239, v[216:217], off
	s_mov_b32 s46, 0x40000
	v_lshl_add_u64 v[218:219], v[200:201], 0, s[46:47]
	global_load_dword v239, v[218:219], off
	global_load_dword v239, v[254:255], off offset:1024
	s_mov_b32 s46, 0x9000
	v_lshl_add_u64 v[220:221], v[236:237], 0, s[46:47]
	global_load_dword v239, v[220:221], off
	s_mov_b32 s46, 0x48000
	v_lshl_add_u64 v[222:223], v[200:201], 0, s[46:47]
	global_load_dword v239, v[222:223], off
	global_load_dword v239, v[254:255], off offset:2048
	s_mov_b32 s46, 0xa000
	v_lshl_add_u64 v[224:225], v[236:237], 0, s[46:47]
	global_load_dword v239, v[224:225], off
	s_mov_b32 s46, 0x50000
	v_lshl_add_u64 v[226:227], v[200:201], 0, s[46:47]
	global_load_dword v239, v[226:227], off
	global_load_dword v239, v[254:255], off offset:3072
	s_mov_b32 s46, 0xb000
	v_lshl_add_u64 v[228:229], v[236:237], 0, s[46:47]
	global_load_dword v239, v[228:229], off
	s_mov_b32 s46, 0x58000
	v_lshl_add_u64 v[230:231], v[200:201], 0, s[46:47]
	global_load_dword v239, v[230:231], off
	v_and_b32_e32 v170, 64, v169
	v_xor_b32_e32 v155, 16, v169
	v_add_u32_e32 v170, 64, v170
	v_xor_b32_e32 v171, 32, v169
	v_cmp_lt_i32_e32 vcc, v155, v170
	v_mov_b64_e32 v[156:157], s[20:21]
	v_lshl_add_u64 v[150:151], s[64:65], 0, v[150:151]
	v_cndmask_b32_e32 v155, v169, v155, vcc
	v_cmp_lt_i32_e32 vcc, v171, v170
	v_lshlrev_b32_e32 v170, 2, v155
	s_waitcnt vmcnt(21)
	v_mov_b64_e32 v[240:241], v[188:189]
	v_mov_b64_e32 v[242:243], v[190:191]
	v_mov_b64_e32 v[244:245], v[192:193]
	v_mov_b64_e32 v[246:247], v[194:195]
	s_mov_b32 s46, 0x400
	v_lshl_add_u64 v[248:249], v[202:203], 0, s[46:47]
	s_mov_b32 s46, 0x1000
	v_lshl_add_u64 v[250:251], v[236:237], 0, s[46:47]
	s_mov_b32 s46, 0x8000
	v_lshl_add_u64 v[252:253], v[200:201], 0, s[46:47]
	global_load_dwordx4 v[220:223], v[248:249], off
	global_load_dwordx4 v[224:227], v[250:251], off
	global_load_dwordx4 v[228:231], v[250:251], off offset:16
	global_load_dwordx4 v[232:235], v[252:253], off
	v_mov_b32_e32 v198, v173
	v_mov_b32_e32 v199, v174
	v_mov_b32_e32 v173, v175
	v_cndmask_b32_e32 v171, v169, v171, vcc
	v_pk_add_f32 v[172:173], v[198:199], v[172:173]
	v_lshlrev_b32_e32 v155, 2, v171
	v_add_f32_e32 v171, v172, v173
	ds_bpermute_b32 v198, v170, v171
	v_lshlrev_b32_e32 v174, 16, v176
	v_mov_b32_e32 v172, v180
	v_mov_b32_e32 v173, v184
	v_mov_b32_e32 v184, v181
	v_mov_b32_e32 v181, v186
	v_mov_b32_e32 v186, v183
	s_waitcnt lgkmcnt(0)
	v_add_f32_e32 v183, v171, v198
	v_pk_add_f32 v[172:173], v[172:173], v[184:185]
	ds_bpermute_b32 v185, v155, v183
	v_mov_b32_e32 v180, v182
	v_pk_add_f32 v[180:181], v[180:181], v[186:187]
	v_and_b32_e32 v175, 0xffff0000, v176
	v_pk_add_f32 v[172:173], v[172:173], v[180:181]
	v_lshlrev_b32_e32 v176, 16, v177
	v_mov_b32_e32 v182, v172
	v_mov_b32_e32 v184, v173
	s_waitcnt lgkmcnt(0)
	v_pk_add_f32 v[172:173], v[182:183], v[184:185]
	v_and_b32_e32 v177, 0xffff0000, v177
	v_pk_fma_f32 v[172:173], v[172:173], s[18:19], v[156:157] op_sel_hi:[1,1,0]
	s_nop 0
	v_mul_f32_e32 v171, 0x4b800000, v173
	v_cmp_gt_f32_e32 vcc, s60, v173
	v_mul_f32_e32 v180, 0x4b800000, v172
	v_cmp_gt_f32_e64 s[4:5], s60, v172
	v_cndmask_b32_e32 v171, v173, v171, vcc
	v_rsq_f32_e32 v171, v171
	v_cndmask_b32_e64 v172, v172, v180, s[4:5]
	v_rsq_f32_e32 v180, v172
	v_lshlrev_b32_e32 v172, 16, v178
	v_and_b32_e32 v173, 0xffff0000, v178
	v_mul_f32_e32 v178, 0x45800000, v171
	v_mul_f32_e32 v181, 0x45800000, v180
	v_cndmask_b32_e32 v178, v171, v178, vcc
	v_cndmask_b32_e64 v180, v180, v181, s[4:5]
	v_pk_mul_f32 v[126:127], v[126:127], v[178:179] op_sel_hi:[1,0]
	v_pk_mul_f32 v[128:129], v[128:129], v[178:179] op_sel_hi:[1,0]
	v_pk_mul_f32 v[124:125], v[124:125], v[178:179] op_sel_hi:[1,0]
	v_pk_mul_f32 v[122:123], v[122:123], v[178:179] op_sel_hi:[1,0]
	v_pk_mul_f32 v[120:121], v[120:121], v[178:179] op_sel_hi:[1,0]
	v_pk_mul_f32 v[118:119], v[118:119], v[178:179] op_sel_hi:[1,0]
	v_pk_mul_f32 v[182:183], v[116:117], v[178:179] op_sel_hi:[1,0]
	v_pk_mul_f32 v[184:185], v[114:115], v[178:179] op_sel_hi:[1,0]
	v_pk_mul_f32 v[116:117], v[188:189], v[180:181] op_sel_hi:[1,0]
	v_mul_f32_e32 v171, 0xbfb8aa3b, v126
	v_mul_f32_e32 v178, 0xbfb8aa3b, v127
	v_pk_mul_f32 v[114:115], v[190:191], v[180:181] op_sel_hi:[1,0]
	v_pk_mul_f32 v[116:117], v[116:117], v[174:175]
	v_mul_f32_e32 v174, 0xbfb8aa3b, v128
	v_mul_f32_e32 v175, 0xbfb8aa3b, v129
	v_exp_f32_e32 v171, v171
	v_exp_f32_e32 v178, v178
	v_pk_mul_f32 v[114:115], v[114:115], v[176:177]
	v_mul_f32_e32 v176, 0xbfb8aa3b, v122
	v_mul_f32_e32 v177, 0xbfb8aa3b, v123
	v_exp_f32_e32 v174, v174
	v_exp_f32_e32 v175, v175
	v_exp_f32_e32 v176, v176
	v_exp_f32_e32 v177, v177
	v_pk_mul_f32 v[186:187], v[194:195], v[180:181] op_sel_hi:[1,0]
	v_pk_mul_f32 v[180:181], v[192:193], v[180:181] op_sel_hi:[1,0]
	v_add_f32_e32 v171, 1.0, v171
	v_add_f32_e32 v178, 1.0, v178
	v_pk_mul_f32 v[172:173], v[180:181], v[172:173]
	v_add_f32_e32 v180, 1.0, v174
	v_add_f32_e32 v181, 1.0, v175
	v_rcp_f32_e32 v174, v171
	v_rcp_f32_e32 v175, v178
	v_add_f32_e32 v188, 1.0, v176
	v_add_f32_e32 v189, 1.0, v177
	v_rcp_f32_e32 v176, v180
	v_rcp_f32_e32 v177, v181
	v_pk_mul_f32 v[126:127], v[126:127], v[174:175]
	v_rcp_f32_e32 v180, v188
	v_rcp_f32_e32 v181, v189
	v_mul_f32_e32 v171, 0xbfb8aa3b, v124
	v_pk_mul_f32 v[128:129], v[128:129], v[176:177]
	v_pk_mul_f32 v[116:117], v[116:117], v[126:127]
	v_pk_mul_f32 v[126:127], v[114:115], v[128:129]
	v_cvt_pk_bf16_f32 v114, v116, v117
	v_exp_f32_e32 v117, v171
	v_mul_f32_e32 v116, 0xbfb8aa3b, v125
	v_cvt_pk_bf16_f32 v115, v126, v127
	v_exp_f32_e32 v126, v116
	v_pk_mul_f32 v[122:123], v[122:123], v[180:181]
	v_add_f32_e32 v117, 1.0, v117
	v_pk_mul_f32 v[122:123], v[172:173], v[122:123]
	v_mul_f32_e32 v118, 0xbfb8aa3b, v118
	v_cvt_pk_bf16_f32 v116, v122, v123
	v_rcp_f32_e32 v122, v117
	v_add_f32_e32 v117, 1.0, v126
	v_rcp_f32_e32 v123, v117
	v_mul_f32_e32 v119, 0xbfb8aa3b, v119
	v_lshlrev_b32_e32 v126, 16, v179
	v_and_b32_e32 v127, 0xffff0000, v179
	v_exp_f32_e32 v118, v118
	v_exp_f32_e32 v119, v119
	v_pk_mul_f32 v[126:127], v[186:187], v[126:127]
	v_pk_mul_f32 v[122:123], v[124:125], v[122:123]
	s_nop 0
	v_pk_mul_f32 v[122:123], v[126:127], v[122:123]
	s_nop 0
	v_cvt_pk_bf16_f32 v117, v122, v123
	global_store_dwordx4 v[196:197], v[114:117], off
	s_nop 1
	v_add_f32_e32 v114, 1.0, v118
	v_add_f32_e32 v115, 1.0, v119
	v_mul_f32_e32 v116, 0xbfb8aa3b, v120
	v_mul_f32_e32 v117, 0xbfb8aa3b, v121
	v_mul_f32_e32 v118, 0xbfb8aa3b, v184
	v_mul_f32_e32 v119, 0xbfb8aa3b, v185
	v_exp_f32_e32 v116, v116
	v_exp_f32_e32 v117, v117
	v_exp_f32_e32 v118, v118
	v_exp_f32_e32 v119, v119
	v_mul_f32_e32 v120, 0xbfb8aa3b, v182
	v_mul_f32_e32 v121, 0xbfb8aa3b, v183
	v_exp_f32_e32 v120, v120
	v_exp_f32_e32 v121, v121
	v_add_f32_e32 v116, 1.0, v116
	v_add_f32_e32 v117, 1.0, v117
	v_add_f32_e32 v118, 1.0, v118
	v_add_f32_e32 v119, 1.0, v119
	v_rcp_f32_e32 v114, v114
	v_rcp_f32_e32 v115, v115
	v_rcp_f32_e32 v116, v116
	v_rcp_f32_e32 v117, v117
	v_rcp_f32_e32 v118, v118
	v_rcp_f32_e32 v119, v119
	v_add_f32_e32 v120, 1.0, v120
	v_add_f32_e32 v121, 1.0, v121
	v_rcp_f32_e32 v120, v120
	v_rcp_f32_e32 v121, v121
	v_cvt_pk_bf16_f32 v114, v114, v115
	v_cvt_pk_bf16_f32 v115, v116, v117
	v_cvt_pk_bf16_f32 v116, v118, v119
	v_lshl_add_u64 v[118:119], v[150:151], 0, v[158:159]
	v_or_b32_e32 v158, 16, v154
	v_cvt_pk_bf16_f32 v117, v120, v121
	v_ashrrev_i32_e32 v159, 31, v158
	global_store_dwordx4 v[118:119], v[114:117], off
	v_lshlrev_b64 v[118:119], 8, v[158:159]
	v_lshl_add_u64 v[122:123], s[44:45], 0, v[118:119]
	v_lshlrev_b64 v[114:115], 6, v[158:159]
	v_lshl_add_u64 v[114:115], v[138:139], 0, v[114:115]
	s_nop 0
	s_nop 0
	s_nop 0
	v_lshlrev_b64 v[158:159], 11, v[158:159]
	v_lshl_add_u64 v[180:181], v[152:153], 0, v[158:159]
	s_waitcnt vmcnt(2)
	v_mov_b64_e32 v[114:115], v[220:221]
	v_mov_b64_e32 v[116:117], v[222:223]
	v_mov_b64_e32 v[118:119], v[224:225]
	v_mov_b64_e32 v[120:121], v[226:227]
	v_mov_b64_e32 v[122:123], v[228:229]
	v_mov_b64_e32 v[124:125], v[230:231]
	v_mov_b64_e32 v[176:177], v[232:233]
	v_mov_b64_e32 v[178:179], v[234:235]
	v_mov_b64_e32 v[126:127], v[240:241]
	v_mov_b64_e32 v[128:129], v[242:243]
	v_mov_b64_e32 v[172:173], v[244:245]
	v_mov_b64_e32 v[174:175], v[246:247]
	s_mov_b32 s46, 0x800
	v_lshl_add_u64 v[248:249], v[202:203], 0, s[46:47]
	s_mov_b32 s46, 0x2000
	v_lshl_add_u64 v[250:251], v[236:237], 0, s[46:47]
	s_mov_b32 s46, 0x10000
	v_lshl_add_u64 v[252:253], v[200:201], 0, s[46:47]
	global_load_dwordx4 v[204:207], v[248:249], off
	global_load_dwordx4 v[208:211], v[250:251], off
	global_load_dwordx4 v[212:215], v[250:251], off offset:16
	global_load_dwordx4 v[216:219], v[252:253], off
	v_mov_b32_e32 v182, v115
	v_mov_b32_e32 v183, v116
	v_mov_b32_e32 v115, v117
	v_pk_add_f32 v[114:115], v[182:183], v[114:115]
	v_mov_b32_e32 v116, v118
	v_add_f32_e32 v118, v114, v115
	v_mov_b32_e32 v117, v122
	v_mov_b32_e32 v122, v119
	ds_bpermute_b32 v119, v170, v118
	v_mov_b32_e32 v115, v124
	v_mov_b32_e32 v124, v121
	v_mov_b32_e32 v114, v120
	v_pk_add_f32 v[116:117], v[116:117], v[122:123]
	s_waitcnt lgkmcnt(0)
	v_add_f32_e32 v119, v118, v119
	ds_bpermute_b32 v121, v155, v119
	v_pk_add_f32 v[114:115], v[114:115], v[124:125]
	v_and_b32_e32 v125, 0xffff0000, v176
	v_pk_add_f32 v[114:115], v[116:117], v[114:115]
	s_nop 0
	v_mov_b32_e32 v118, v114
	v_mov_b32_e32 v120, v115
	s_waitcnt lgkmcnt(0)
	v_pk_add_f32 v[114:115], v[118:119], v[120:121]
	s_nop 0
	v_pk_fma_f32 v[114:115], v[114:115], s[18:19], v[156:157] op_sel_hi:[1,1,0]
	s_nop 0
	v_mul_f32_e32 v116, 0x4b800000, v115
	v_cmp_gt_f32_e32 vcc, s60, v115
	v_mul_f32_e32 v117, 0x4b800000, v114
	v_cmp_gt_f32_e64 s[4:5], s60, v114
	v_cndmask_b32_e32 v115, v115, v116, vcc
	v_rsq_f32_e32 v115, v115
	v_cndmask_b32_e64 v114, v114, v117, s[4:5]
	v_rsq_f32_e32 v118, v114
	v_mul_f32_e32 v114, 0x45800000, v115
	v_cndmask_b32_e32 v114, v115, v114, vcc
	v_pk_mul_f32 v[112:113], v[112:113], v[114:115] op_sel_hi:[1,0]
	v_pk_mul_f32 v[110:111], v[110:111], v[114:115] op_sel_hi:[1,0]
	v_pk_mul_f32 v[108:109], v[108:109], v[114:115] op_sel_hi:[1,0]
	v_pk_mul_f32 v[106:107], v[106:107], v[114:115] op_sel_hi:[1,0]
	v_pk_mul_f32 v[104:105], v[104:105], v[114:115] op_sel_hi:[1,0]
	v_pk_mul_f32 v[102:103], v[102:103], v[114:115] op_sel_hi:[1,0]
	v_pk_mul_f32 v[116:117], v[100:101], v[114:115] op_sel_hi:[1,0]
	v_pk_mul_f32 v[114:115], v[98:99], v[114:115] op_sel_hi:[1,0]
	v_mul_f32_e32 v98, 0x45800000, v118
	v_cndmask_b32_e64 v98, v118, v98, s[4:5]
	v_pk_mul_f32 v[100:101], v[128:129], v[98:99] op_sel_hi:[1,0]
	v_pk_mul_f32 v[118:119], v[126:127], v[98:99] op_sel_hi:[1,0]
	v_pk_mul_f32 v[120:121], v[174:175], v[98:99] op_sel_hi:[1,0]
	v_mul_f32_e32 v99, 0xbfb8aa3b, v110
	v_mul_f32_e32 v122, 0xbfb8aa3b, v111
	v_exp_f32_e32 v99, v99
	v_exp_f32_e32 v124, v122
	v_mul_f32_e32 v102, 0xbfb8aa3b, v102
	v_mul_f32_e32 v103, 0xbfb8aa3b, v103
	v_pk_mul_f32 v[122:123], v[172:173], v[98:99] op_sel_hi:[1,0]
	v_add_f32_e32 v98, 1.0, v99
	v_add_f32_e32 v99, 1.0, v124
	v_rcp_f32_e32 v98, v98
	v_rcp_f32_e32 v99, v99
	v_lshlrev_b32_e32 v124, 16, v176
	v_pk_mul_f32 v[118:119], v[118:119], v[124:125]
	v_exp_f32_e32 v102, v102
	v_pk_mul_f32 v[98:99], v[110:111], v[98:99]
	v_mul_f32_e32 v110, 0xbfb8aa3b, v112
	v_exp_f32_e32 v110, v110
	v_mul_f32_e32 v111, 0xbfb8aa3b, v113
	v_exp_f32_e32 v111, v111
	v_pk_mul_f32 v[98:99], v[118:119], v[98:99]
	v_lshlrev_b32_e32 v118, 16, v177
	v_cvt_pk_bf16_f32 v98, v98, v99
	v_add_f32_e32 v99, 1.0, v110
	v_rcp_f32_e32 v110, v99
	v_add_f32_e32 v99, 1.0, v111
	v_rcp_f32_e32 v111, v99
	v_and_b32_e32 v119, 0xffff0000, v177
	v_pk_mul_f32 v[100:101], v[100:101], v[118:119]
	v_mul_f32_e32 v99, 0xbfb8aa3b, v106
	v_pk_mul_f32 v[110:111], v[112:113], v[110:111]
	v_exp_f32_e32 v103, v103
	v_pk_mul_f32 v[100:101], v[100:101], v[110:111]
	v_exp_f32_e32 v110, v99
	v_mul_f32_e32 v99, 0xbfb8aa3b, v107
	v_exp_f32_e32 v111, v99
	v_cvt_pk_bf16_f32 v99, v100, v101
	v_add_f32_e32 v100, 1.0, v110
	v_rcp_f32_e32 v100, v100
	v_add_f32_e32 v101, 1.0, v111
	v_rcp_f32_e32 v101, v101
	v_lshlrev_b32_e32 v110, 16, v178
	v_and_b32_e32 v111, 0xffff0000, v178
	v_pk_mul_f32 v[110:111], v[122:123], v[110:111]
	v_pk_mul_f32 v[100:101], v[106:107], v[100:101]
	v_mul_f32_e32 v106, 0xbfb8aa3b, v108
	v_exp_f32_e32 v106, v106
	v_mul_f32_e32 v107, 0xbfb8aa3b, v109
	v_exp_f32_e32 v107, v107
	v_pk_mul_f32 v[100:101], v[110:111], v[100:101]
	v_lshlrev_b32_e32 v110, 16, v179
	v_cvt_pk_bf16_f32 v100, v100, v101
	v_add_f32_e32 v101, 1.0, v106
	v_rcp_f32_e32 v106, v101
	v_add_f32_e32 v101, 1.0, v107
	v_rcp_f32_e32 v107, v101
	v_and_b32_e32 v111, 0xffff0000, v179
	v_pk_mul_f32 v[110:111], v[120:121], v[110:111]
	v_or_b32_e32 v118, 32, v154
	v_pk_mul_f32 v[106:107], v[108:109], v[106:107]
	v_ashrrev_i32_e32 v119, 31, v118
	v_pk_mul_f32 v[106:107], v[110:111], v[106:107]
	v_lshlrev_b64 v[122:123], 11, v[118:119]
	v_cvt_pk_bf16_f32 v101, v106, v107
	global_store_dwordx4 v[180:181], v[98:101], off
	v_lshl_add_u64 v[124:125], v[152:153], 0, v[122:123]
	s_nop 0
	v_add_f32_e32 v98, 1.0, v102
	v_add_f32_e32 v99, 1.0, v103
	v_mul_f32_e32 v100, 0xbfb8aa3b, v104
	v_mul_f32_e32 v101, 0xbfb8aa3b, v105
	v_mul_f32_e32 v102, 0xbfb8aa3b, v114
	v_mul_f32_e32 v103, 0xbfb8aa3b, v115
	v_mul_f32_e32 v104, 0xbfb8aa3b, v116
	v_mul_f32_e32 v105, 0xbfb8aa3b, v117
	v_exp_f32_e32 v100, v100
	v_exp_f32_e32 v101, v101
	v_exp_f32_e32 v102, v102
	v_exp_f32_e32 v103, v103
	v_exp_f32_e32 v104, v104
	v_exp_f32_e32 v105, v105
	v_add_f32_e32 v100, 1.0, v100
	v_add_f32_e32 v101, 1.0, v101
	v_add_f32_e32 v102, 1.0, v102
	v_add_f32_e32 v103, 1.0, v103
	v_add_f32_e32 v104, 1.0, v104
	v_add_f32_e32 v105, 1.0, v105
	v_rcp_f32_e32 v98, v98
	v_rcp_f32_e32 v99, v99
	v_rcp_f32_e32 v100, v100
	v_rcp_f32_e32 v101, v101
	v_rcp_f32_e32 v102, v102
	v_rcp_f32_e32 v103, v103
	v_rcp_f32_e32 v104, v104
	v_rcp_f32_e32 v105, v105
	v_cvt_pk_bf16_f32 v98, v98, v99
	v_cvt_pk_bf16_f32 v99, v100, v101
	v_cvt_pk_bf16_f32 v100, v102, v103
	v_cvt_pk_bf16_f32 v101, v104, v105
	v_lshl_add_u64 v[102:103], v[150:151], 0, v[158:159]
	global_store_dwordx4 v[102:103], v[98:101], off
	v_lshlrev_b64 v[102:103], 8, v[118:119]
	v_lshl_add_u64 v[106:107], s[44:45], 0, v[102:103]
	v_lshlrev_b64 v[98:99], 6, v[118:119]
	v_lshl_add_u64 v[98:99], v[138:139], 0, v[98:99]
	s_nop 0
	s_nop 0
	s_nop 0
	s_waitcnt vmcnt(2)
	v_mov_b64_e32 v[98:99], v[204:205]
	v_mov_b64_e32 v[100:101], v[206:207]
	v_mov_b64_e32 v[102:103], v[208:209]
	v_mov_b64_e32 v[104:105], v[210:211]
	v_mov_b64_e32 v[106:107], v[212:213]
	v_mov_b64_e32 v[108:109], v[214:215]
	v_mov_b64_e32 v[118:119], v[216:217]
	v_mov_b64_e32 v[120:121], v[218:219]
	v_mov_b64_e32 v[110:111], v[240:241]
	v_mov_b64_e32 v[112:113], v[242:243]
	v_mov_b64_e32 v[114:115], v[244:245]
	v_mov_b64_e32 v[116:117], v[246:247]
	s_mov_b32 s46, 0xc00
	v_lshl_add_u64 v[248:249], v[202:203], 0, s[46:47]
	s_mov_b32 s46, 0x3000
	v_lshl_add_u64 v[250:251], v[236:237], 0, s[46:47]
	s_mov_b32 s46, 0x18000
	v_lshl_add_u64 v[252:253], v[200:201], 0, s[46:47]
	global_load_dwordx4 v[220:223], v[248:249], off
	global_load_dwordx4 v[224:227], v[250:251], off
	global_load_dwordx4 v[228:231], v[250:251], off offset:16
	global_load_dwordx4 v[232:235], v[252:253], off
	v_mov_b32_e32 v126, v99
	v_mov_b32_e32 v127, v100
	v_mov_b32_e32 v99, v101
	v_pk_add_f32 v[98:99], v[126:127], v[98:99]
	v_mov_b32_e32 v126, v102
	v_add_f32_e32 v98, v98, v99
	ds_bpermute_b32 v99, v170, v98
	v_mov_b32_e32 v127, v106
	v_mov_b32_e32 v106, v103
	v_pk_add_f32 v[102:103], v[126:127], v[106:107]
	v_mov_b32_e32 v106, v104
	s_waitcnt lgkmcnt(0)
	v_add_f32_e32 v99, v98, v99
	ds_bpermute_b32 v101, v155, v99
	v_mov_b32_e32 v107, v108
	v_mov_b32_e32 v108, v105
	v_pk_add_f32 v[104:105], v[106:107], v[108:109]
	v_and_b32_e32 v109, 0xffff0000, v118
	v_pk_add_f32 v[102:103], v[102:103], v[104:105]
	s_nop 0
	v_mov_b32_e32 v98, v102
	v_mov_b32_e32 v100, v103
	s_waitcnt lgkmcnt(0)
	v_pk_add_f32 v[98:99], v[98:99], v[100:101]
	s_nop 0
	v_pk_fma_f32 v[98:99], v[98:99], s[18:19], v[156:157] op_sel_hi:[1,1,0]
	s_nop 0
	v_mul_f32_e32 v100, 0x4b800000, v99
	v_cmp_gt_f32_e32 vcc, s60, v99
	s_nop 1
	v_cndmask_b32_e32 v99, v99, v100, vcc
	v_rsq_f32_e32 v99, v99
	s_nop 0
	v_mul_f32_e32 v100, 0x45800000, v99
	v_cndmask_b32_e32 v100, v99, v100, vcc
	v_mul_f32_e32 v99, 0x4b800000, v98
	v_cmp_gt_f32_e32 vcc, s60, v98
	v_pk_mul_f32 v[96:97], v[96:97], v[100:101] op_sel_hi:[1,0]
	v_pk_mul_f32 v[94:95], v[94:95], v[100:101] op_sel_hi:[1,0]
	v_cndmask_b32_e32 v98, v98, v99, vcc
	v_rsq_f32_e32 v102, v98
	v_pk_mul_f32 v[92:93], v[92:93], v[100:101] op_sel_hi:[1,0]
	v_pk_mul_f32 v[90:91], v[90:91], v[100:101] op_sel_hi:[1,0]
	v_pk_mul_f32 v[88:89], v[88:89], v[100:101] op_sel_hi:[1,0]
	v_pk_mul_f32 v[86:87], v[86:87], v[100:101] op_sel_hi:[1,0]
	v_pk_mul_f32 v[98:99], v[84:85], v[100:101] op_sel_hi:[1,0]
	v_pk_mul_f32 v[100:101], v[82:83], v[100:101] op_sel_hi:[1,0]
	v_mul_f32_e32 v82, 0x45800000, v102
	v_cndmask_b32_e32 v82, v102, v82, vcc
	v_pk_mul_f32 v[84:85], v[112:113], v[82:83] op_sel_hi:[1,0]
	v_pk_mul_f32 v[102:103], v[110:111], v[82:83] op_sel_hi:[1,0]
	v_pk_mul_f32 v[104:105], v[116:117], v[82:83] op_sel_hi:[1,0]
	v_mul_f32_e32 v83, 0xbfb8aa3b, v94
	v_mul_f32_e32 v106, 0xbfb8aa3b, v95
	v_exp_f32_e32 v83, v83
	v_exp_f32_e32 v108, v106
	v_mul_f32_e32 v86, 0xbfb8aa3b, v86
	v_mul_f32_e32 v87, 0xbfb8aa3b, v87
	v_pk_mul_f32 v[106:107], v[114:115], v[82:83] op_sel_hi:[1,0]
	v_add_f32_e32 v82, 1.0, v83
	v_add_f32_e32 v83, 1.0, v108
	v_rcp_f32_e32 v82, v82
	v_rcp_f32_e32 v83, v83
	v_lshlrev_b32_e32 v108, 16, v118
	v_pk_mul_f32 v[102:103], v[102:103], v[108:109]
	v_exp_f32_e32 v86, v86
	v_pk_mul_f32 v[82:83], v[94:95], v[82:83]
	v_mul_f32_e32 v94, 0xbfb8aa3b, v96
	v_exp_f32_e32 v94, v94
	v_mul_f32_e32 v95, 0xbfb8aa3b, v97
	v_exp_f32_e32 v95, v95
	v_pk_mul_f32 v[82:83], v[102:103], v[82:83]
	v_lshlrev_b32_e32 v102, 16, v119
	v_cvt_pk_bf16_f32 v82, v82, v83
	v_add_f32_e32 v83, 1.0, v94
	v_rcp_f32_e32 v94, v83
	v_add_f32_e32 v83, 1.0, v95
	v_rcp_f32_e32 v95, v83
	v_and_b32_e32 v103, 0xffff0000, v119
	v_pk_mul_f32 v[84:85], v[84:85], v[102:103]
	v_mul_f32_e32 v83, 0xbfb8aa3b, v90
	v_pk_mul_f32 v[94:95], v[96:97], v[94:95]
	v_exp_f32_e32 v87, v87
	v_pk_mul_f32 v[84:85], v[84:85], v[94:95]
	v_exp_f32_e32 v94, v83
	v_mul_f32_e32 v83, 0xbfb8aa3b, v91
	v_exp_f32_e32 v95, v83
	v_cvt_pk_bf16_f32 v83, v84, v85
	v_add_f32_e32 v84, 1.0, v94
	v_rcp_f32_e32 v84, v84
	v_add_f32_e32 v85, 1.0, v95
	v_rcp_f32_e32 v85, v85
	v_lshlrev_b32_e32 v94, 16, v120
	v_and_b32_e32 v95, 0xffff0000, v120
	v_pk_mul_f32 v[94:95], v[106:107], v[94:95]
	v_pk_mul_f32 v[84:85], v[90:91], v[84:85]
	v_mul_f32_e32 v90, 0xbfb8aa3b, v92
	v_exp_f32_e32 v90, v90
	v_mul_f32_e32 v91, 0xbfb8aa3b, v93
	v_exp_f32_e32 v91, v91
	v_pk_mul_f32 v[84:85], v[94:95], v[84:85]
	v_lshlrev_b32_e32 v94, 16, v121
	v_cvt_pk_bf16_f32 v84, v84, v85
	v_add_f32_e32 v85, 1.0, v90
	v_rcp_f32_e32 v90, v85
	v_add_f32_e32 v85, 1.0, v91
	v_rcp_f32_e32 v91, v85
	v_and_b32_e32 v95, 0xffff0000, v121
	v_pk_mul_f32 v[94:95], v[104:105], v[94:95]
	v_or_b32_e32 v102, 48, v154
	v_pk_mul_f32 v[90:91], v[92:93], v[90:91]
	v_ashrrev_i32_e32 v103, 31, v102
	v_pk_mul_f32 v[90:91], v[94:95], v[90:91]
	v_lshlrev_b64 v[106:107], 11, v[102:103]
	v_cvt_pk_bf16_f32 v85, v90, v91
	global_store_dwordx4 v[124:125], v[82:85], off
	v_lshl_add_u64 v[108:109], v[152:153], 0, v[106:107]
	s_nop 0
	v_add_f32_e32 v82, 1.0, v86
	v_add_f32_e32 v83, 1.0, v87
	v_mul_f32_e32 v84, 0xbfb8aa3b, v88
	v_mul_f32_e32 v85, 0xbfb8aa3b, v89
	v_mul_f32_e32 v86, 0xbfb8aa3b, v100
	v_mul_f32_e32 v87, 0xbfb8aa3b, v101
	v_mul_f32_e32 v88, 0xbfb8aa3b, v98
	v_mul_f32_e32 v89, 0xbfb8aa3b, v99
	v_exp_f32_e32 v84, v84
	v_exp_f32_e32 v85, v85
	v_exp_f32_e32 v86, v86
	v_exp_f32_e32 v87, v87
	v_exp_f32_e32 v88, v88
	v_exp_f32_e32 v89, v89
	v_add_f32_e32 v84, 1.0, v84
	v_add_f32_e32 v85, 1.0, v85
	v_add_f32_e32 v86, 1.0, v86
	v_add_f32_e32 v87, 1.0, v87
	v_add_f32_e32 v88, 1.0, v88
	v_add_f32_e32 v89, 1.0, v89
	v_rcp_f32_e32 v82, v82
	v_rcp_f32_e32 v83, v83
	v_rcp_f32_e32 v84, v84
	v_rcp_f32_e32 v85, v85
	v_rcp_f32_e32 v86, v86
	v_rcp_f32_e32 v87, v87
	v_rcp_f32_e32 v88, v88
	v_rcp_f32_e32 v89, v89
	v_cvt_pk_bf16_f32 v82, v82, v83
	v_cvt_pk_bf16_f32 v83, v84, v85
	v_cvt_pk_bf16_f32 v84, v86, v87
	v_cvt_pk_bf16_f32 v85, v88, v89
	v_lshl_add_u64 v[86:87], v[150:151], 0, v[122:123]
	global_store_dwordx4 v[86:87], v[82:85], off
	v_lshlrev_b64 v[86:87], 8, v[102:103]
	v_lshl_add_u64 v[90:91], s[44:45], 0, v[86:87]
	v_lshlrev_b64 v[82:83], 6, v[102:103]
	v_lshl_add_u64 v[82:83], v[138:139], 0, v[82:83]
	s_nop 0
	s_nop 0
	s_nop 0
	s_waitcnt vmcnt(2)
	v_mov_b64_e32 v[82:83], v[220:221]
	v_mov_b64_e32 v[84:85], v[222:223]
	v_mov_b64_e32 v[86:87], v[224:225]
	v_mov_b64_e32 v[88:89], v[226:227]
	v_mov_b64_e32 v[90:91], v[228:229]
	v_mov_b64_e32 v[92:93], v[230:231]
	v_mov_b64_e32 v[102:103], v[232:233]
	v_mov_b64_e32 v[104:105], v[234:235]
	v_mov_b64_e32 v[94:95], v[240:241]
	v_mov_b64_e32 v[96:97], v[242:243]
	v_mov_b64_e32 v[98:99], v[244:245]
	v_mov_b64_e32 v[100:101], v[246:247]
	s_mov_b32 s46, 0x2000
	v_lshl_add_u64 v[248:249], v[202:203], 0, s[46:47]
	s_mov_b32 s46, 0x8000
	v_lshl_add_u64 v[250:251], v[236:237], 0, s[46:47]
	s_mov_b32 s46, 0x40000
	v_lshl_add_u64 v[252:253], v[200:201], 0, s[46:47]
	global_load_dwordx4 v[204:207], v[248:249], off
	global_load_dwordx4 v[208:211], v[250:251], off
	global_load_dwordx4 v[212:215], v[250:251], off offset:16
	global_load_dwordx4 v[216:219], v[252:253], off
	v_mov_b32_e32 v110, v83
	v_mov_b32_e32 v111, v84
	v_mov_b32_e32 v83, v85
	v_pk_add_f32 v[82:83], v[110:111], v[82:83]
	v_mov_b32_e32 v110, v86
	v_add_f32_e32 v82, v82, v83
	ds_bpermute_b32 v83, v170, v82
	v_mov_b32_e32 v111, v90
	v_mov_b32_e32 v90, v87
	v_pk_add_f32 v[86:87], v[110:111], v[90:91]
	v_mov_b32_e32 v90, v88
	s_waitcnt lgkmcnt(0)
	v_add_f32_e32 v83, v82, v83
	ds_bpermute_b32 v85, v155, v83
	v_mov_b32_e32 v91, v92
	v_mov_b32_e32 v92, v89
	v_pk_add_f32 v[88:89], v[90:91], v[92:93]
	v_and_b32_e32 v93, 0xffff0000, v102
	v_pk_add_f32 v[86:87], v[86:87], v[88:89]
	s_nop 0
	v_mov_b32_e32 v82, v86
	v_mov_b32_e32 v84, v87
	s_waitcnt lgkmcnt(0)
	v_pk_add_f32 v[82:83], v[82:83], v[84:85]
	s_nop 0
	v_pk_fma_f32 v[82:83], v[82:83], s[18:19], v[156:157] op_sel_hi:[1,1,0]
	s_nop 0
	v_mul_f32_e32 v84, 0x4b800000, v83
	v_cmp_gt_f32_e32 vcc, s60, v83
	s_nop 1
	v_cndmask_b32_e32 v83, v83, v84, vcc
	v_rsq_f32_e32 v83, v83
	s_nop 0
	v_mul_f32_e32 v84, 0x45800000, v83
	v_cndmask_b32_e32 v84, v83, v84, vcc
	v_mul_f32_e32 v83, 0x4b800000, v82
	v_cmp_gt_f32_e32 vcc, s60, v82
	v_pk_mul_f32 v[80:81], v[80:81], v[84:85] op_sel_hi:[1,0]
	v_pk_mul_f32 v[78:79], v[78:79], v[84:85] op_sel_hi:[1,0]
	v_cndmask_b32_e32 v82, v82, v83, vcc
	v_rsq_f32_e32 v86, v82
	v_pk_mul_f32 v[76:77], v[76:77], v[84:85] op_sel_hi:[1,0]
	v_pk_mul_f32 v[74:75], v[74:75], v[84:85] op_sel_hi:[1,0]
	v_pk_mul_f32 v[72:73], v[72:73], v[84:85] op_sel_hi:[1,0]
	v_pk_mul_f32 v[70:71], v[70:71], v[84:85] op_sel_hi:[1,0]
	v_pk_mul_f32 v[82:83], v[68:69], v[84:85] op_sel_hi:[1,0]
	v_pk_mul_f32 v[84:85], v[66:67], v[84:85] op_sel_hi:[1,0]
	v_mul_f32_e32 v66, 0x45800000, v86
	v_cndmask_b32_e32 v66, v86, v66, vcc
	v_pk_mul_f32 v[68:69], v[96:97], v[66:67] op_sel_hi:[1,0]
	v_pk_mul_f32 v[86:87], v[94:95], v[66:67] op_sel_hi:[1,0]
	v_pk_mul_f32 v[88:89], v[100:101], v[66:67] op_sel_hi:[1,0]
	v_mul_f32_e32 v67, 0xbfb8aa3b, v78
	v_mul_f32_e32 v90, 0xbfb8aa3b, v79
	v_exp_f32_e32 v67, v67
	v_exp_f32_e32 v92, v90
	v_mul_f32_e32 v70, 0xbfb8aa3b, v70
	v_mul_f32_e32 v71, 0xbfb8aa3b, v71
	v_pk_mul_f32 v[90:91], v[98:99], v[66:67] op_sel_hi:[1,0]
	v_add_f32_e32 v66, 1.0, v67
	v_add_f32_e32 v67, 1.0, v92
	v_rcp_f32_e32 v66, v66
	v_rcp_f32_e32 v67, v67
	v_lshlrev_b32_e32 v92, 16, v102
	v_pk_mul_f32 v[86:87], v[86:87], v[92:93]
	v_exp_f32_e32 v70, v70
	v_pk_mul_f32 v[66:67], v[78:79], v[66:67]
	v_mul_f32_e32 v78, 0xbfb8aa3b, v80
	v_exp_f32_e32 v78, v78
	v_mul_f32_e32 v79, 0xbfb8aa3b, v81
	v_exp_f32_e32 v79, v79
	v_pk_mul_f32 v[66:67], v[86:87], v[66:67]
	v_lshlrev_b32_e32 v86, 16, v103
	v_cvt_pk_bf16_f32 v66, v66, v67
	v_add_f32_e32 v67, 1.0, v78
	v_rcp_f32_e32 v78, v67
	v_add_f32_e32 v67, 1.0, v79
	v_rcp_f32_e32 v79, v67
	v_and_b32_e32 v87, 0xffff0000, v103
	v_pk_mul_f32 v[68:69], v[68:69], v[86:87]
	v_mul_f32_e32 v67, 0xbfb8aa3b, v74
	v_pk_mul_f32 v[78:79], v[80:81], v[78:79]
	v_exp_f32_e32 v71, v71
	v_pk_mul_f32 v[68:69], v[68:69], v[78:79]
	v_exp_f32_e32 v78, v67
	v_mul_f32_e32 v67, 0xbfb8aa3b, v75
	v_exp_f32_e32 v79, v67
	v_cvt_pk_bf16_f32 v67, v68, v69
	v_add_f32_e32 v68, 1.0, v78
	v_rcp_f32_e32 v68, v68
	v_add_f32_e32 v69, 1.0, v79
	v_rcp_f32_e32 v69, v69
	v_lshlrev_b32_e32 v78, 16, v104
	v_and_b32_e32 v79, 0xffff0000, v104
	v_pk_mul_f32 v[78:79], v[90:91], v[78:79]
	v_pk_mul_f32 v[68:69], v[74:75], v[68:69]
	v_mul_f32_e32 v74, 0xbfb8aa3b, v76
	v_exp_f32_e32 v74, v74
	v_mul_f32_e32 v75, 0xbfb8aa3b, v77
	v_exp_f32_e32 v75, v75
	v_pk_mul_f32 v[68:69], v[78:79], v[68:69]
	v_lshlrev_b32_e32 v78, 16, v105
	v_cvt_pk_bf16_f32 v68, v68, v69
	v_add_f32_e32 v69, 1.0, v74
	v_rcp_f32_e32 v74, v69
	v_add_f32_e32 v69, 1.0, v75
	v_rcp_f32_e32 v75, v69
	v_and_b32_e32 v79, 0xffff0000, v105
	v_pk_mul_f32 v[78:79], v[88:89], v[78:79]
	v_add_u32_e32 v86, 0x80, v154
	v_pk_mul_f32 v[74:75], v[76:77], v[74:75]
	v_ashrrev_i32_e32 v87, 31, v86
	v_pk_mul_f32 v[74:75], v[78:79], v[74:75]
	v_lshlrev_b64 v[90:91], 11, v[86:87]
	v_cvt_pk_bf16_f32 v69, v74, v75
	global_store_dwordx4 v[108:109], v[66:69], off
	v_lshl_add_u64 v[92:93], v[152:153], 0, v[90:91]
	s_nop 0
	v_add_f32_e32 v66, 1.0, v70
	v_add_f32_e32 v67, 1.0, v71
	v_mul_f32_e32 v68, 0xbfb8aa3b, v72
	v_mul_f32_e32 v69, 0xbfb8aa3b, v73
	v_mul_f32_e32 v70, 0xbfb8aa3b, v84
	v_mul_f32_e32 v71, 0xbfb8aa3b, v85
	v_mul_f32_e32 v72, 0xbfb8aa3b, v82
	v_mul_f32_e32 v73, 0xbfb8aa3b, v83
	v_exp_f32_e32 v68, v68
	v_exp_f32_e32 v69, v69
	v_exp_f32_e32 v70, v70
	v_exp_f32_e32 v71, v71
	v_exp_f32_e32 v72, v72
	v_exp_f32_e32 v73, v73
	v_add_f32_e32 v68, 1.0, v68
	v_add_f32_e32 v69, 1.0, v69
	v_add_f32_e32 v70, 1.0, v70
	v_add_f32_e32 v71, 1.0, v71
	v_add_f32_e32 v72, 1.0, v72
	v_add_f32_e32 v73, 1.0, v73
	v_rcp_f32_e32 v66, v66
	v_rcp_f32_e32 v67, v67
	v_rcp_f32_e32 v68, v68
	v_rcp_f32_e32 v69, v69
	v_rcp_f32_e32 v70, v70
	v_rcp_f32_e32 v71, v71
	v_rcp_f32_e32 v72, v72
	v_rcp_f32_e32 v73, v73
	v_cvt_pk_bf16_f32 v66, v66, v67
	v_cvt_pk_bf16_f32 v67, v68, v69
	v_cvt_pk_bf16_f32 v68, v70, v71
	v_cvt_pk_bf16_f32 v69, v72, v73
	v_lshl_add_u64 v[70:71], v[150:151], 0, v[106:107]
	global_store_dwordx4 v[70:71], v[66:69], off
	v_lshlrev_b64 v[70:71], 8, v[86:87]
	v_lshl_add_u64 v[74:75], s[44:45], 0, v[70:71]
	v_lshlrev_b64 v[66:67], 6, v[86:87]
	v_lshl_add_u64 v[66:67], v[138:139], 0, v[66:67]
	s_nop 0
	s_nop 0
	s_nop 0
	s_waitcnt vmcnt(2)
	v_mov_b64_e32 v[66:67], v[204:205]
	v_mov_b64_e32 v[68:69], v[206:207]
	v_mov_b64_e32 v[70:71], v[208:209]
	v_mov_b64_e32 v[72:73], v[210:211]
	v_mov_b64_e32 v[74:75], v[212:213]
	v_mov_b64_e32 v[76:77], v[214:215]
	v_mov_b64_e32 v[86:87], v[216:217]
	v_mov_b64_e32 v[88:89], v[218:219]
	v_mov_b64_e32 v[78:79], v[240:241]
	v_mov_b64_e32 v[80:81], v[242:243]
	v_mov_b64_e32 v[82:83], v[244:245]
	v_mov_b64_e32 v[84:85], v[246:247]
	s_mov_b32 s46, 0x2400
	v_lshl_add_u64 v[248:249], v[202:203], 0, s[46:47]
	s_mov_b32 s46, 0x9000
	v_lshl_add_u64 v[250:251], v[236:237], 0, s[46:47]
	s_mov_b32 s46, 0x48000
	v_lshl_add_u64 v[252:253], v[200:201], 0, s[46:47]
	global_load_dwordx4 v[220:223], v[248:249], off
	global_load_dwordx4 v[224:227], v[250:251], off
	global_load_dwordx4 v[228:231], v[250:251], off offset:16
	global_load_dwordx4 v[232:235], v[252:253], off
	v_mov_b32_e32 v94, v67
	v_mov_b32_e32 v95, v68
	v_mov_b32_e32 v67, v69
	v_pk_add_f32 v[66:67], v[94:95], v[66:67]
	v_mov_b32_e32 v94, v70
	v_add_f32_e32 v66, v66, v67
	ds_bpermute_b32 v67, v170, v66
	v_mov_b32_e32 v95, v74
	v_mov_b32_e32 v74, v71
	v_pk_add_f32 v[70:71], v[94:95], v[74:75]
	v_mov_b32_e32 v74, v72
	s_waitcnt lgkmcnt(0)
	v_add_f32_e32 v67, v66, v67
	ds_bpermute_b32 v69, v155, v67
	v_mov_b32_e32 v75, v76
	v_mov_b32_e32 v76, v73
	v_pk_add_f32 v[72:73], v[74:75], v[76:77]
	v_and_b32_e32 v77, 0xffff0000, v86
	v_pk_add_f32 v[70:71], v[70:71], v[72:73]
	s_nop 0
	v_mov_b32_e32 v66, v70
	v_mov_b32_e32 v68, v71
	s_waitcnt lgkmcnt(0)
	v_pk_add_f32 v[66:67], v[66:67], v[68:69]
	s_nop 0
	v_pk_fma_f32 v[66:67], v[66:67], s[18:19], v[156:157] op_sel_hi:[1,1,0]
	s_nop 0
	v_mul_f32_e32 v68, 0x4b800000, v67
	v_cmp_gt_f32_e32 vcc, s60, v67
	s_nop 1
	v_cndmask_b32_e32 v67, v67, v68, vcc
	v_rsq_f32_e32 v67, v67
	s_nop 0
	v_mul_f32_e32 v68, 0x45800000, v67
	v_cndmask_b32_e32 v68, v67, v68, vcc
	v_mul_f32_e32 v67, 0x4b800000, v66
	v_cmp_gt_f32_e32 vcc, s60, v66
	v_pk_mul_f32 v[64:65], v[64:65], v[68:69] op_sel_hi:[1,0]
	v_pk_mul_f32 v[62:63], v[62:63], v[68:69] op_sel_hi:[1,0]
	v_cndmask_b32_e32 v66, v66, v67, vcc
	v_rsq_f32_e32 v70, v66
	v_pk_mul_f32 v[60:61], v[60:61], v[68:69] op_sel_hi:[1,0]
	v_pk_mul_f32 v[58:59], v[58:59], v[68:69] op_sel_hi:[1,0]
	v_pk_mul_f32 v[56:57], v[56:57], v[68:69] op_sel_hi:[1,0]
	v_pk_mul_f32 v[54:55], v[54:55], v[68:69] op_sel_hi:[1,0]
	v_pk_mul_f32 v[66:67], v[52:53], v[68:69] op_sel_hi:[1,0]
	v_pk_mul_f32 v[68:69], v[50:51], v[68:69] op_sel_hi:[1,0]
	v_mul_f32_e32 v50, 0x45800000, v70
	v_cndmask_b32_e32 v50, v70, v50, vcc
	v_pk_mul_f32 v[52:53], v[80:81], v[50:51] op_sel_hi:[1,0]
	v_pk_mul_f32 v[70:71], v[78:79], v[50:51] op_sel_hi:[1,0]
	v_pk_mul_f32 v[72:73], v[84:85], v[50:51] op_sel_hi:[1,0]
	v_mul_f32_e32 v51, 0xbfb8aa3b, v62
	v_mul_f32_e32 v74, 0xbfb8aa3b, v63
	v_exp_f32_e32 v51, v51
	v_exp_f32_e32 v76, v74
	v_mul_f32_e32 v54, 0xbfb8aa3b, v54
	v_mul_f32_e32 v55, 0xbfb8aa3b, v55
	v_pk_mul_f32 v[74:75], v[82:83], v[50:51] op_sel_hi:[1,0]
	v_add_f32_e32 v50, 1.0, v51
	v_add_f32_e32 v51, 1.0, v76
	v_rcp_f32_e32 v50, v50
	v_rcp_f32_e32 v51, v51
	v_lshlrev_b32_e32 v76, 16, v86
	v_pk_mul_f32 v[70:71], v[70:71], v[76:77]
	v_exp_f32_e32 v54, v54
	v_pk_mul_f32 v[50:51], v[62:63], v[50:51]
	v_mul_f32_e32 v62, 0xbfb8aa3b, v64
	v_exp_f32_e32 v62, v62
	v_mul_f32_e32 v63, 0xbfb8aa3b, v65
	v_exp_f32_e32 v63, v63
	v_pk_mul_f32 v[50:51], v[70:71], v[50:51]
	v_lshlrev_b32_e32 v70, 16, v87
	v_cvt_pk_bf16_f32 v50, v50, v51
	v_add_f32_e32 v51, 1.0, v62
	v_rcp_f32_e32 v62, v51
	v_add_f32_e32 v51, 1.0, v63
	v_rcp_f32_e32 v63, v51
	v_and_b32_e32 v71, 0xffff0000, v87
	v_pk_mul_f32 v[52:53], v[52:53], v[70:71]
	v_mul_f32_e32 v51, 0xbfb8aa3b, v58
	v_pk_mul_f32 v[62:63], v[64:65], v[62:63]
	v_exp_f32_e32 v55, v55
	v_pk_mul_f32 v[52:53], v[52:53], v[62:63]
	v_exp_f32_e32 v62, v51
	v_mul_f32_e32 v51, 0xbfb8aa3b, v59
	v_exp_f32_e32 v63, v51
	v_cvt_pk_bf16_f32 v51, v52, v53
	v_add_f32_e32 v52, 1.0, v62
	v_rcp_f32_e32 v52, v52
	v_add_f32_e32 v53, 1.0, v63
	v_rcp_f32_e32 v53, v53
	v_lshlrev_b32_e32 v62, 16, v88
	v_and_b32_e32 v63, 0xffff0000, v88
	v_pk_mul_f32 v[62:63], v[74:75], v[62:63]
	v_pk_mul_f32 v[52:53], v[58:59], v[52:53]
	v_mul_f32_e32 v58, 0xbfb8aa3b, v60
	v_exp_f32_e32 v58, v58
	v_mul_f32_e32 v59, 0xbfb8aa3b, v61
	v_exp_f32_e32 v59, v59
	v_pk_mul_f32 v[52:53], v[62:63], v[52:53]
	v_lshlrev_b32_e32 v62, 16, v89
	v_cvt_pk_bf16_f32 v52, v52, v53
	v_add_f32_e32 v53, 1.0, v58
	v_rcp_f32_e32 v58, v53
	v_add_f32_e32 v53, 1.0, v59
	v_rcp_f32_e32 v59, v53
	v_and_b32_e32 v63, 0xffff0000, v89
	v_pk_mul_f32 v[62:63], v[72:73], v[62:63]
	v_add_u32_e32 v70, 0x90, v154
	v_pk_mul_f32 v[58:59], v[60:61], v[58:59]
	v_ashrrev_i32_e32 v71, 31, v70
	v_pk_mul_f32 v[58:59], v[62:63], v[58:59]
	v_lshlrev_b64 v[74:75], 11, v[70:71]
	v_cvt_pk_bf16_f32 v53, v58, v59
	global_store_dwordx4 v[92:93], v[50:53], off
	v_lshl_add_u64 v[76:77], v[152:153], 0, v[74:75]
	s_nop 0
	v_add_f32_e32 v50, 1.0, v54
	v_add_f32_e32 v51, 1.0, v55
	v_mul_f32_e32 v52, 0xbfb8aa3b, v56
	v_mul_f32_e32 v53, 0xbfb8aa3b, v57
	v_mul_f32_e32 v54, 0xbfb8aa3b, v68
	v_mul_f32_e32 v55, 0xbfb8aa3b, v69
	v_mul_f32_e32 v56, 0xbfb8aa3b, v66
	v_mul_f32_e32 v57, 0xbfb8aa3b, v67
	v_exp_f32_e32 v52, v52
	v_exp_f32_e32 v53, v53
	v_exp_f32_e32 v54, v54
	v_exp_f32_e32 v55, v55
	v_exp_f32_e32 v56, v56
	v_exp_f32_e32 v57, v57
	v_add_f32_e32 v52, 1.0, v52
	v_add_f32_e32 v53, 1.0, v53
	v_add_f32_e32 v54, 1.0, v54
	v_add_f32_e32 v55, 1.0, v55
	v_add_f32_e32 v56, 1.0, v56
	v_add_f32_e32 v57, 1.0, v57
	v_rcp_f32_e32 v50, v50
	v_rcp_f32_e32 v51, v51
	v_rcp_f32_e32 v52, v52
	v_rcp_f32_e32 v53, v53
	v_rcp_f32_e32 v54, v54
	v_rcp_f32_e32 v55, v55
	v_rcp_f32_e32 v56, v56
	v_rcp_f32_e32 v57, v57
	v_cvt_pk_bf16_f32 v50, v50, v51
	v_cvt_pk_bf16_f32 v51, v52, v53
	v_cvt_pk_bf16_f32 v52, v54, v55
	v_cvt_pk_bf16_f32 v53, v56, v57
	v_lshl_add_u64 v[54:55], v[150:151], 0, v[90:91]
	global_store_dwordx4 v[54:55], v[50:53], off
	v_lshlrev_b64 v[54:55], 8, v[70:71]
	v_lshl_add_u64 v[58:59], s[44:45], 0, v[54:55]
	v_lshlrev_b64 v[50:51], 6, v[70:71]
	v_lshl_add_u64 v[50:51], v[138:139], 0, v[50:51]
	s_nop 0
	s_nop 0
	s_nop 0
	s_waitcnt vmcnt(2)
	v_mov_b64_e32 v[50:51], v[220:221]
	v_mov_b64_e32 v[52:53], v[222:223]
	v_mov_b64_e32 v[54:55], v[224:225]
	v_mov_b64_e32 v[56:57], v[226:227]
	v_mov_b64_e32 v[58:59], v[228:229]
	v_mov_b64_e32 v[60:61], v[230:231]
	v_mov_b64_e32 v[70:71], v[232:233]
	v_mov_b64_e32 v[72:73], v[234:235]
	v_mov_b64_e32 v[62:63], v[240:241]
	v_mov_b64_e32 v[64:65], v[242:243]
	v_mov_b64_e32 v[66:67], v[244:245]
	v_mov_b64_e32 v[68:69], v[246:247]
	s_mov_b32 s46, 0x2800
	v_lshl_add_u64 v[248:249], v[202:203], 0, s[46:47]
	s_mov_b32 s46, 0xa000
	v_lshl_add_u64 v[250:251], v[236:237], 0, s[46:47]
	s_mov_b32 s46, 0x50000
	v_lshl_add_u64 v[252:253], v[200:201], 0, s[46:47]
	global_load_dwordx4 v[204:207], v[248:249], off
	global_load_dwordx4 v[208:211], v[250:251], off
	global_load_dwordx4 v[212:215], v[250:251], off offset:16
	global_load_dwordx4 v[216:219], v[252:253], off
	v_mov_b32_e32 v78, v51
	v_mov_b32_e32 v79, v52
	v_mov_b32_e32 v51, v53
	v_pk_add_f32 v[50:51], v[78:79], v[50:51]
	v_mov_b32_e32 v78, v54
	v_add_f32_e32 v50, v50, v51
	ds_bpermute_b32 v51, v170, v50
	v_mov_b32_e32 v79, v58
	v_mov_b32_e32 v58, v55
	v_pk_add_f32 v[54:55], v[78:79], v[58:59]
	v_mov_b32_e32 v58, v56
	s_waitcnt lgkmcnt(0)
	v_add_f32_e32 v51, v50, v51
	ds_bpermute_b32 v53, v155, v51
	v_mov_b32_e32 v59, v60
	v_mov_b32_e32 v60, v57
	v_pk_add_f32 v[56:57], v[58:59], v[60:61]
	v_and_b32_e32 v61, 0xffff0000, v70
	v_pk_add_f32 v[54:55], v[54:55], v[56:57]
	s_nop 0
	v_mov_b32_e32 v50, v54
	v_mov_b32_e32 v52, v55
	s_waitcnt lgkmcnt(0)
	v_pk_add_f32 v[50:51], v[50:51], v[52:53]
	s_nop 0
	v_pk_fma_f32 v[50:51], v[50:51], s[18:19], v[156:157] op_sel_hi:[1,1,0]
	s_nop 0
	v_mul_f32_e32 v52, 0x4b800000, v51
	v_cmp_gt_f32_e32 vcc, s60, v51
	s_nop 1
	v_cndmask_b32_e32 v51, v51, v52, vcc
	v_rsq_f32_e32 v51, v51
	s_nop 0
	v_mul_f32_e32 v52, 0x45800000, v51
	v_cndmask_b32_e32 v52, v51, v52, vcc
	v_mul_f32_e32 v51, 0x4b800000, v50
	v_cmp_gt_f32_e32 vcc, s60, v50
	v_pk_mul_f32 v[48:49], v[48:49], v[52:53] op_sel_hi:[1,0]
	v_pk_mul_f32 v[46:47], v[46:47], v[52:53] op_sel_hi:[1,0]
	v_cndmask_b32_e32 v50, v50, v51, vcc
	v_rsq_f32_e32 v54, v50
	v_pk_mul_f32 v[44:45], v[44:45], v[52:53] op_sel_hi:[1,0]
	v_pk_mul_f32 v[42:43], v[42:43], v[52:53] op_sel_hi:[1,0]
	v_pk_mul_f32 v[40:41], v[40:41], v[52:53] op_sel_hi:[1,0]
	v_pk_mul_f32 v[38:39], v[38:39], v[52:53] op_sel_hi:[1,0]
	v_pk_mul_f32 v[50:51], v[36:37], v[52:53] op_sel_hi:[1,0]
	v_pk_mul_f32 v[52:53], v[34:35], v[52:53] op_sel_hi:[1,0]
	v_mul_f32_e32 v34, 0x45800000, v54
	v_cndmask_b32_e32 v34, v54, v34, vcc
	v_pk_mul_f32 v[36:37], v[64:65], v[34:35] op_sel_hi:[1,0]
	v_pk_mul_f32 v[54:55], v[62:63], v[34:35] op_sel_hi:[1,0]
	v_pk_mul_f32 v[56:57], v[68:69], v[34:35] op_sel_hi:[1,0]
	v_mul_f32_e32 v35, 0xbfb8aa3b, v46
	v_mul_f32_e32 v58, 0xbfb8aa3b, v47
	v_exp_f32_e32 v35, v35
	v_exp_f32_e32 v60, v58
	v_mul_f32_e32 v38, 0xbfb8aa3b, v38
	v_mul_f32_e32 v39, 0xbfb8aa3b, v39
	v_pk_mul_f32 v[58:59], v[66:67], v[34:35] op_sel_hi:[1,0]
	v_add_f32_e32 v34, 1.0, v35
	v_add_f32_e32 v35, 1.0, v60
	v_rcp_f32_e32 v34, v34
	v_rcp_f32_e32 v35, v35
	v_lshlrev_b32_e32 v60, 16, v70
	v_pk_mul_f32 v[54:55], v[54:55], v[60:61]
	v_exp_f32_e32 v38, v38
	v_pk_mul_f32 v[34:35], v[46:47], v[34:35]
	v_mul_f32_e32 v46, 0xbfb8aa3b, v48
	v_exp_f32_e32 v46, v46
	v_mul_f32_e32 v47, 0xbfb8aa3b, v49
	v_exp_f32_e32 v47, v47
	v_pk_mul_f32 v[34:35], v[54:55], v[34:35]
	v_lshlrev_b32_e32 v54, 16, v71
	v_cvt_pk_bf16_f32 v34, v34, v35
	v_add_f32_e32 v35, 1.0, v46
	v_rcp_f32_e32 v46, v35
	v_add_f32_e32 v35, 1.0, v47
	v_rcp_f32_e32 v47, v35
	v_and_b32_e32 v55, 0xffff0000, v71
	v_pk_mul_f32 v[36:37], v[36:37], v[54:55]
	v_mul_f32_e32 v35, 0xbfb8aa3b, v42
	v_pk_mul_f32 v[46:47], v[48:49], v[46:47]
	v_exp_f32_e32 v39, v39
	v_pk_mul_f32 v[36:37], v[36:37], v[46:47]
	v_exp_f32_e32 v46, v35
	v_mul_f32_e32 v35, 0xbfb8aa3b, v43
	v_exp_f32_e32 v47, v35
	v_cvt_pk_bf16_f32 v35, v36, v37
	v_add_f32_e32 v36, 1.0, v46
	v_rcp_f32_e32 v36, v36
	v_add_f32_e32 v37, 1.0, v47
	v_rcp_f32_e32 v37, v37
	v_lshlrev_b32_e32 v46, 16, v72
	v_and_b32_e32 v47, 0xffff0000, v72
	v_pk_mul_f32 v[46:47], v[58:59], v[46:47]
	v_pk_mul_f32 v[36:37], v[42:43], v[36:37]
	v_mul_f32_e32 v42, 0xbfb8aa3b, v44
	v_exp_f32_e32 v42, v42
	v_mul_f32_e32 v43, 0xbfb8aa3b, v45
	v_exp_f32_e32 v43, v43
	v_pk_mul_f32 v[36:37], v[46:47], v[36:37]
	v_lshlrev_b32_e32 v46, 16, v73
	v_cvt_pk_bf16_f32 v36, v36, v37
	v_add_f32_e32 v37, 1.0, v42
	v_rcp_f32_e32 v42, v37
	v_add_f32_e32 v37, 1.0, v43
	v_rcp_f32_e32 v43, v37
	v_and_b32_e32 v47, 0xffff0000, v73
	v_pk_mul_f32 v[46:47], v[56:57], v[46:47]
	v_add_u32_e32 v54, 0xa0, v154
	v_pk_mul_f32 v[42:43], v[44:45], v[42:43]
	v_ashrrev_i32_e32 v55, 31, v54
	v_pk_mul_f32 v[42:43], v[46:47], v[42:43]
	v_lshlrev_b64 v[58:59], 11, v[54:55]
	v_cvt_pk_bf16_f32 v37, v42, v43
	global_store_dwordx4 v[76:77], v[34:37], off
	v_lshl_add_u64 v[60:61], v[152:153], 0, v[58:59]
	s_nop 0
	v_add_f32_e32 v34, 1.0, v38
	v_add_f32_e32 v35, 1.0, v39
	v_mul_f32_e32 v36, 0xbfb8aa3b, v40
	v_mul_f32_e32 v37, 0xbfb8aa3b, v41
	v_mul_f32_e32 v38, 0xbfb8aa3b, v52
	v_mul_f32_e32 v39, 0xbfb8aa3b, v53
	v_mul_f32_e32 v40, 0xbfb8aa3b, v50
	v_mul_f32_e32 v41, 0xbfb8aa3b, v51
	v_exp_f32_e32 v36, v36
	v_exp_f32_e32 v37, v37
	v_exp_f32_e32 v38, v38
	v_exp_f32_e32 v39, v39
	v_exp_f32_e32 v40, v40
	v_exp_f32_e32 v41, v41
	v_add_f32_e32 v36, 1.0, v36
	v_add_f32_e32 v37, 1.0, v37
	v_add_f32_e32 v38, 1.0, v38
	v_add_f32_e32 v39, 1.0, v39
	v_add_f32_e32 v40, 1.0, v40
	v_add_f32_e32 v41, 1.0, v41
	v_rcp_f32_e32 v34, v34
	v_rcp_f32_e32 v35, v35
	v_rcp_f32_e32 v36, v36
	v_rcp_f32_e32 v37, v37
	v_rcp_f32_e32 v38, v38
	v_rcp_f32_e32 v39, v39
	v_rcp_f32_e32 v40, v40
	v_rcp_f32_e32 v41, v41
	v_cvt_pk_bf16_f32 v34, v34, v35
	v_cvt_pk_bf16_f32 v35, v36, v37
	v_cvt_pk_bf16_f32 v36, v38, v39
	v_cvt_pk_bf16_f32 v37, v40, v41
	v_lshl_add_u64 v[38:39], v[150:151], 0, v[74:75]
	global_store_dwordx4 v[38:39], v[34:37], off
	v_lshlrev_b64 v[38:39], 8, v[54:55]
	v_lshl_add_u64 v[42:43], s[44:45], 0, v[38:39]
	v_lshlrev_b64 v[34:35], 6, v[54:55]
	v_lshl_add_u64 v[34:35], v[138:139], 0, v[34:35]
	s_nop 0
	s_nop 0
	s_nop 0
	s_waitcnt vmcnt(2)
	v_mov_b64_e32 v[34:35], v[204:205]
	v_mov_b64_e32 v[36:37], v[206:207]
	v_mov_b64_e32 v[38:39], v[208:209]
	v_mov_b64_e32 v[40:41], v[210:211]
	v_mov_b64_e32 v[42:43], v[212:213]
	v_mov_b64_e32 v[44:45], v[214:215]
	v_mov_b64_e32 v[54:55], v[216:217]
	v_mov_b64_e32 v[56:57], v[218:219]
	v_mov_b64_e32 v[46:47], v[240:241]
	v_mov_b64_e32 v[48:49], v[242:243]
	v_mov_b64_e32 v[50:51], v[244:245]
	v_mov_b64_e32 v[52:53], v[246:247]
	s_mov_b32 s46, 0x2c00
	v_lshl_add_u64 v[248:249], v[202:203], 0, s[46:47]
	s_mov_b32 s46, 0xb000
	v_lshl_add_u64 v[250:251], v[236:237], 0, s[46:47]
	s_mov_b32 s46, 0x58000
	v_lshl_add_u64 v[252:253], v[200:201], 0, s[46:47]
	global_load_dwordx4 v[220:223], v[248:249], off
	global_load_dwordx4 v[224:227], v[250:251], off
	global_load_dwordx4 v[228:231], v[250:251], off offset:16
	global_load_dwordx4 v[232:235], v[252:253], off
	v_mov_b32_e32 v62, v35
	v_mov_b32_e32 v63, v36
	v_mov_b32_e32 v35, v37
	v_pk_add_f32 v[34:35], v[62:63], v[34:35]
	v_mov_b32_e32 v62, v38
	v_add_f32_e32 v34, v34, v35
	ds_bpermute_b32 v35, v170, v34
	v_mov_b32_e32 v63, v42
	v_mov_b32_e32 v42, v39
	v_pk_add_f32 v[38:39], v[62:63], v[42:43]
	v_mov_b32_e32 v42, v40
	s_waitcnt lgkmcnt(0)
	v_add_f32_e32 v35, v34, v35
	ds_bpermute_b32 v37, v155, v35
	v_mov_b32_e32 v43, v44
	v_mov_b32_e32 v44, v41
	v_pk_add_f32 v[40:41], v[42:43], v[44:45]
	v_and_b32_e32 v45, 0xffff0000, v54
	v_pk_add_f32 v[38:39], v[38:39], v[40:41]
	s_nop 0
	v_mov_b32_e32 v34, v38
	v_mov_b32_e32 v36, v39
	s_waitcnt lgkmcnt(0)
	v_pk_add_f32 v[34:35], v[34:35], v[36:37]
	s_nop 0
	v_pk_fma_f32 v[34:35], v[34:35], s[18:19], v[156:157] op_sel_hi:[1,1,0]
	s_nop 0
	v_mul_f32_e32 v36, 0x4b800000, v35
	v_cmp_gt_f32_e32 vcc, s60, v35
	s_nop 1
	v_cndmask_b32_e32 v35, v35, v36, vcc
	v_rsq_f32_e32 v35, v35
	s_nop 0
	v_mul_f32_e32 v36, 0x45800000, v35
	v_cndmask_b32_e32 v36, v35, v36, vcc
	v_mul_f32_e32 v35, 0x4b800000, v34
	v_cmp_gt_f32_e32 vcc, s60, v34
	v_pk_mul_f32 v[32:33], v[32:33], v[36:37] op_sel_hi:[1,0]
	v_pk_mul_f32 v[30:31], v[30:31], v[36:37] op_sel_hi:[1,0]
	v_cndmask_b32_e32 v34, v34, v35, vcc
	v_rsq_f32_e32 v38, v34
	v_pk_mul_f32 v[28:29], v[28:29], v[36:37] op_sel_hi:[1,0]
	v_pk_mul_f32 v[26:27], v[26:27], v[36:37] op_sel_hi:[1,0]
	v_pk_mul_f32 v[24:25], v[24:25], v[36:37] op_sel_hi:[1,0]
	v_pk_mul_f32 v[22:23], v[22:23], v[36:37] op_sel_hi:[1,0]
	v_pk_mul_f32 v[34:35], v[20:21], v[36:37] op_sel_hi:[1,0]
	v_pk_mul_f32 v[36:37], v[18:19], v[36:37] op_sel_hi:[1,0]
	v_mul_f32_e32 v18, 0x45800000, v38
	v_cndmask_b32_e32 v18, v38, v18, vcc
	v_pk_mul_f32 v[20:21], v[48:49], v[18:19] op_sel_hi:[1,0]
	v_pk_mul_f32 v[38:39], v[46:47], v[18:19] op_sel_hi:[1,0]
	v_pk_mul_f32 v[40:41], v[52:53], v[18:19] op_sel_hi:[1,0]
	v_mul_f32_e32 v19, 0xbfb8aa3b, v30
	v_mul_f32_e32 v42, 0xbfb8aa3b, v31
	v_exp_f32_e32 v19, v19
	v_exp_f32_e32 v44, v42
	v_mul_f32_e32 v22, 0xbfb8aa3b, v22
	v_mul_f32_e32 v23, 0xbfb8aa3b, v23
	v_pk_mul_f32 v[42:43], v[50:51], v[18:19] op_sel_hi:[1,0]
	v_add_f32_e32 v18, 1.0, v19
	v_add_f32_e32 v19, 1.0, v44
	v_rcp_f32_e32 v18, v18
	v_rcp_f32_e32 v19, v19
	v_lshlrev_b32_e32 v44, 16, v54
	v_pk_mul_f32 v[38:39], v[38:39], v[44:45]
	v_exp_f32_e32 v22, v22
	v_pk_mul_f32 v[18:19], v[30:31], v[18:19]
	v_mul_f32_e32 v30, 0xbfb8aa3b, v32
	v_exp_f32_e32 v30, v30
	v_mul_f32_e32 v31, 0xbfb8aa3b, v33
	v_exp_f32_e32 v31, v31
	v_pk_mul_f32 v[18:19], v[38:39], v[18:19]
	v_lshlrev_b32_e32 v38, 16, v55
	v_cvt_pk_bf16_f32 v18, v18, v19
	v_add_f32_e32 v19, 1.0, v30
	v_rcp_f32_e32 v30, v19
	v_add_f32_e32 v19, 1.0, v31
	v_rcp_f32_e32 v31, v19
	v_and_b32_e32 v39, 0xffff0000, v55
	v_pk_mul_f32 v[20:21], v[20:21], v[38:39]
	v_mul_f32_e32 v19, 0xbfb8aa3b, v26
	v_pk_mul_f32 v[30:31], v[32:33], v[30:31]
	v_exp_f32_e32 v23, v23
	v_pk_mul_f32 v[20:21], v[20:21], v[30:31]
	v_exp_f32_e32 v30, v19
	v_mul_f32_e32 v19, 0xbfb8aa3b, v27
	v_exp_f32_e32 v31, v19
	v_cvt_pk_bf16_f32 v19, v20, v21
	v_add_f32_e32 v20, 1.0, v30
	v_rcp_f32_e32 v20, v20
	v_add_f32_e32 v21, 1.0, v31
	v_rcp_f32_e32 v21, v21
	v_lshlrev_b32_e32 v30, 16, v56
	v_and_b32_e32 v31, 0xffff0000, v56
	v_pk_mul_f32 v[30:31], v[42:43], v[30:31]
	v_pk_mul_f32 v[20:21], v[26:27], v[20:21]
	v_mul_f32_e32 v26, 0xbfb8aa3b, v28
	v_exp_f32_e32 v26, v26
	v_mul_f32_e32 v27, 0xbfb8aa3b, v29
	v_exp_f32_e32 v27, v27
	v_pk_mul_f32 v[20:21], v[30:31], v[20:21]
	v_lshlrev_b32_e32 v30, 16, v57
	v_cvt_pk_bf16_f32 v20, v20, v21
	v_add_f32_e32 v21, 1.0, v26
	v_rcp_f32_e32 v26, v21
	v_add_f32_e32 v21, 1.0, v27
	v_rcp_f32_e32 v27, v21
	v_and_b32_e32 v31, 0xffff0000, v57
	v_pk_mul_f32 v[30:31], v[40:41], v[30:31]
	v_add_u32_e32 v38, 0xb0, v154
	v_pk_mul_f32 v[26:27], v[28:29], v[26:27]
	v_ashrrev_i32_e32 v39, 31, v38
	v_pk_mul_f32 v[26:27], v[30:31], v[26:27]
	v_lshlrev_b64 v[42:43], 11, v[38:39]
	v_cvt_pk_bf16_f32 v21, v26, v27
	global_store_dwordx4 v[60:61], v[18:21], off
	v_lshl_add_u64 v[44:45], v[152:153], 0, v[42:43]
	s_nop 0
	v_add_f32_e32 v18, 1.0, v22
	v_add_f32_e32 v19, 1.0, v23
	v_mul_f32_e32 v20, 0xbfb8aa3b, v24
	v_mul_f32_e32 v21, 0xbfb8aa3b, v25
	v_mul_f32_e32 v22, 0xbfb8aa3b, v36
	v_mul_f32_e32 v23, 0xbfb8aa3b, v37
	v_mul_f32_e32 v24, 0xbfb8aa3b, v34
	v_mul_f32_e32 v25, 0xbfb8aa3b, v35
	v_exp_f32_e32 v20, v20
	v_exp_f32_e32 v21, v21
	v_exp_f32_e32 v22, v22
	v_exp_f32_e32 v23, v23
	v_exp_f32_e32 v24, v24
	v_exp_f32_e32 v25, v25
	v_add_f32_e32 v20, 1.0, v20
	v_add_f32_e32 v21, 1.0, v21
	v_add_f32_e32 v22, 1.0, v22
	v_add_f32_e32 v23, 1.0, v23
	v_add_f32_e32 v24, 1.0, v24
	v_add_f32_e32 v25, 1.0, v25
	v_rcp_f32_e32 v18, v18
	v_rcp_f32_e32 v19, v19
	v_rcp_f32_e32 v20, v20
	v_rcp_f32_e32 v21, v21
	v_rcp_f32_e32 v22, v22
	v_rcp_f32_e32 v23, v23
	v_rcp_f32_e32 v24, v24
	v_rcp_f32_e32 v25, v25
	v_cvt_pk_bf16_f32 v18, v18, v19
	v_cvt_pk_bf16_f32 v19, v20, v21
	v_cvt_pk_bf16_f32 v20, v22, v23
	v_cvt_pk_bf16_f32 v21, v24, v25
	v_lshl_add_u64 v[22:23], v[150:151], 0, v[58:59]
	global_store_dwordx4 v[22:23], v[18:21], off
	v_lshlrev_b64 v[22:23], 8, v[38:39]
	v_lshl_add_u64 v[26:27], s[44:45], 0, v[22:23]
	v_lshlrev_b64 v[18:19], 6, v[38:39]
	v_lshl_add_u64 v[18:19], v[138:139], 0, v[18:19]
	s_nop 0
	s_nop 0
	s_nop 0
	s_waitcnt vmcnt(2)
	v_mov_b64_e32 v[18:19], v[220:221]
	v_mov_b64_e32 v[20:21], v[222:223]
	v_mov_b64_e32 v[22:23], v[224:225]
	v_mov_b64_e32 v[24:25], v[226:227]
	v_mov_b64_e32 v[26:27], v[228:229]
	v_mov_b64_e32 v[28:29], v[230:231]
	v_mov_b64_e32 v[38:39], v[232:233]
	v_mov_b64_e32 v[40:41], v[234:235]
	v_mov_b64_e32 v[30:31], v[240:241]
	v_mov_b64_e32 v[32:33], v[242:243]
	v_mov_b64_e32 v[34:35], v[244:245]
	v_mov_b64_e32 v[36:37], v[246:247]
	v_mov_b32_e32 v46, v19
	v_mov_b32_e32 v47, v20
	v_mov_b32_e32 v19, v21
	v_pk_add_f32 v[18:19], v[46:47], v[18:19]
	v_mov_b32_e32 v46, v22
	v_add_f32_e32 v18, v18, v19
	ds_bpermute_b32 v19, v170, v18
	v_mov_b32_e32 v47, v26
	v_mov_b32_e32 v26, v23
	v_pk_add_f32 v[22:23], v[46:47], v[26:27]
	v_mov_b32_e32 v26, v24
	s_waitcnt lgkmcnt(0)
	v_add_f32_e32 v19, v18, v19
	ds_bpermute_b32 v21, v155, v19
	v_mov_b32_e32 v27, v28
	v_mov_b32_e32 v28, v25
	v_pk_add_f32 v[24:25], v[26:27], v[28:29]
	v_and_b32_e32 v29, 0xffff0000, v38
	v_pk_add_f32 v[22:23], v[22:23], v[24:25]
	s_nop 0
	v_mov_b32_e32 v18, v22
	v_mov_b32_e32 v20, v23
	s_waitcnt lgkmcnt(0)
	v_pk_add_f32 v[18:19], v[18:19], v[20:21]
	s_nop 0
	v_pk_fma_f32 v[18:19], v[18:19], s[18:19], v[156:157] op_sel_hi:[1,1,0]
	s_nop 0
	v_mul_f32_e32 v20, 0x4b800000, v19
	v_cmp_gt_f32_e32 vcc, s60, v19
	s_nop 1
	v_cndmask_b32_e32 v19, v19, v20, vcc
	v_rsq_f32_e32 v19, v19
	s_nop 0
	v_mul_f32_e32 v20, 0x45800000, v19
	v_cndmask_b32_e32 v20, v19, v20, vcc
	v_mul_f32_e32 v19, 0x4b800000, v18
	v_cmp_gt_f32_e32 vcc, s60, v18
	v_pk_mul_f32 v[16:17], v[16:17], v[20:21] op_sel_hi:[1,0]
	v_pk_mul_f32 v[14:15], v[14:15], v[20:21] op_sel_hi:[1,0]
	v_cndmask_b32_e32 v18, v18, v19, vcc
	v_rsq_f32_e32 v22, v18
	v_pk_mul_f32 v[12:13], v[12:13], v[20:21] op_sel_hi:[1,0]
	v_pk_mul_f32 v[10:11], v[10:11], v[20:21] op_sel_hi:[1,0]
	v_pk_mul_f32 v[8:9], v[8:9], v[20:21] op_sel_hi:[1,0]
	v_pk_mul_f32 v[6:7], v[6:7], v[20:21] op_sel_hi:[1,0]
	v_pk_mul_f32 v[18:19], v[4:5], v[20:21] op_sel_hi:[1,0]
	v_pk_mul_f32 v[20:21], v[2:3], v[20:21] op_sel_hi:[1,0]
	v_mul_f32_e32 v2, 0x45800000, v22
	v_cndmask_b32_e32 v2, v22, v2, vcc
	v_pk_mul_f32 v[4:5], v[32:33], v[2:3] op_sel_hi:[1,0]
	v_pk_mul_f32 v[22:23], v[30:31], v[2:3] op_sel_hi:[1,0]
	v_pk_mul_f32 v[24:25], v[36:37], v[2:3] op_sel_hi:[1,0]
	v_mul_f32_e32 v3, 0xbfb8aa3b, v14
	v_mul_f32_e32 v26, 0xbfb8aa3b, v15
	v_exp_f32_e32 v3, v3
	v_exp_f32_e32 v28, v26
	v_mul_f32_e32 v6, 0xbfb8aa3b, v6
	v_mul_f32_e32 v7, 0xbfb8aa3b, v7
	v_pk_mul_f32 v[26:27], v[34:35], v[2:3] op_sel_hi:[1,0]
	v_add_f32_e32 v2, 1.0, v3
	v_add_f32_e32 v3, 1.0, v28
	v_rcp_f32_e32 v2, v2
	v_rcp_f32_e32 v3, v3
	v_lshlrev_b32_e32 v28, 16, v38
	v_pk_mul_f32 v[22:23], v[22:23], v[28:29]
	v_exp_f32_e32 v6, v6
	v_pk_mul_f32 v[2:3], v[14:15], v[2:3]
	v_mul_f32_e32 v14, 0xbfb8aa3b, v16
	v_exp_f32_e32 v14, v14
	v_mul_f32_e32 v15, 0xbfb8aa3b, v17
	v_exp_f32_e32 v15, v15
	v_pk_mul_f32 v[2:3], v[22:23], v[2:3]
	v_lshlrev_b32_e32 v22, 16, v39
	v_cvt_pk_bf16_f32 v2, v2, v3
	v_add_f32_e32 v3, 1.0, v14
	v_rcp_f32_e32 v14, v3
	v_add_f32_e32 v3, 1.0, v15
	v_rcp_f32_e32 v15, v3
	v_and_b32_e32 v23, 0xffff0000, v39
	v_pk_mul_f32 v[4:5], v[4:5], v[22:23]
	v_mul_f32_e32 v3, 0xbfb8aa3b, v10
	v_pk_mul_f32 v[14:15], v[16:17], v[14:15]
	v_exp_f32_e32 v7, v7
	v_pk_mul_f32 v[4:5], v[4:5], v[14:15]
	v_exp_f32_e32 v14, v3
	v_mul_f32_e32 v3, 0xbfb8aa3b, v11
	v_exp_f32_e32 v15, v3
	v_cvt_pk_bf16_f32 v3, v4, v5
	v_add_f32_e32 v4, 1.0, v14
	v_rcp_f32_e32 v4, v4
	v_add_f32_e32 v5, 1.0, v15
	v_rcp_f32_e32 v5, v5
	v_lshlrev_b32_e32 v14, 16, v40
	v_and_b32_e32 v15, 0xffff0000, v40
	v_pk_mul_f32 v[14:15], v[26:27], v[14:15]
	v_pk_mul_f32 v[4:5], v[10:11], v[4:5]
	v_mul_f32_e32 v10, 0xbfb8aa3b, v12
	v_exp_f32_e32 v10, v10
	v_mul_f32_e32 v11, 0xbfb8aa3b, v13
	v_exp_f32_e32 v11, v11
	v_pk_mul_f32 v[4:5], v[14:15], v[4:5]
	v_lshlrev_b32_e32 v14, 16, v41
	v_cvt_pk_bf16_f32 v4, v4, v5
	v_add_f32_e32 v5, 1.0, v10
	v_rcp_f32_e32 v10, v5
	v_add_f32_e32 v5, 1.0, v11
	v_rcp_f32_e32 v11, v5
	v_and_b32_e32 v15, 0xffff0000, v41
	v_pk_mul_f32 v[14:15], v[24:25], v[14:15]
	s_andn2_b64 vcc, exec, s[0:1]
	v_pk_mul_f32 v[10:11], v[12:13], v[10:11]
	s_mov_b64 s[0:1], -1
	v_pk_mul_f32 v[10:11], v[14:15], v[10:11]
	s_nop 0
	v_cvt_pk_bf16_f32 v5, v10, v11
	global_store_dwordx4 v[44:45], v[2:5], off
	s_nop 1
	v_add_f32_e32 v2, 1.0, v6
	v_add_f32_e32 v3, 1.0, v7
	v_mul_f32_e32 v4, 0xbfb8aa3b, v8
	v_mul_f32_e32 v5, 0xbfb8aa3b, v9
	v_mul_f32_e32 v6, 0xbfb8aa3b, v20
	v_mul_f32_e32 v7, 0xbfb8aa3b, v21
	v_mul_f32_e32 v8, 0xbfb8aa3b, v18
	v_mul_f32_e32 v9, 0xbfb8aa3b, v19
	v_exp_f32_e32 v4, v4
	v_exp_f32_e32 v5, v5
	v_exp_f32_e32 v6, v6
	v_exp_f32_e32 v7, v7
	v_exp_f32_e32 v8, v8
	v_exp_f32_e32 v9, v9
	v_add_f32_e32 v4, 1.0, v4
	v_add_f32_e32 v5, 1.0, v5
	v_add_f32_e32 v6, 1.0, v6
	v_add_f32_e32 v7, 1.0, v7
	v_add_f32_e32 v8, 1.0, v8
	v_add_f32_e32 v9, 1.0, v9
	v_rcp_f32_e32 v2, v2
	v_rcp_f32_e32 v3, v3
	v_rcp_f32_e32 v4, v4
	v_rcp_f32_e32 v5, v5
	v_rcp_f32_e32 v6, v6
	v_rcp_f32_e32 v7, v7
	v_rcp_f32_e32 v8, v8
	v_rcp_f32_e32 v9, v9
	v_cvt_pk_bf16_f32 v2, v2, v3
	v_cvt_pk_bf16_f32 v3, v4, v5
	v_cvt_pk_bf16_f32 v4, v6, v7
	v_cvt_pk_bf16_f32 v5, v8, v9
	v_lshl_add_u64 v[6:7], v[150:151], 0, v[42:43]
	global_store_dwordx4 v[6:7], v[2:5], off
	s_cbranch_vccnz .LBB0_2908
	s_andn2_b64 vcc, exec, s[8:9]
	s_cbranch_vccnz .LBB0_2907
	s_barrier
	s_branch .LBB0_2907

	.amdhsa_kernel _Z4mega6Params
		.amdhsa_group_segment_fixed_size 0
		.amdhsa_private_segment_fixed_size 0
		.amdhsa_kernarg_size 480
		.amdhsa_user_sgpr_count 2
		.amdhsa_user_sgpr_dispatch_ptr 0
		.amdhsa_user_sgpr_queue_ptr 0
		.amdhsa_user_sgpr_kernarg_segment_ptr 1
		.amdhsa_user_sgpr_dispatch_id 0
		.amdhsa_user_sgpr_kernarg_preload_length 0
		.amdhsa_user_sgpr_kernarg_preload_offset 0
		.amdhsa_user_sgpr_private_segment_size 0
		.amdhsa_uses_dynamic_stack 0
		.amdhsa_enable_private_segment 0
		.amdhsa_system_sgpr_workgroup_id_x 1
		.amdhsa_system_sgpr_workgroup_id_y 0
		.amdhsa_system_sgpr_workgroup_id_z 0
		.amdhsa_system_sgpr_workgroup_info 0
		.amdhsa_system_vgpr_workitem_id 2
		.amdhsa_next_free_vgpr 256
		.amdhsa_next_free_sgpr 100
		.amdhsa_accum_offset 256
		.amdhsa_reserve_vcc 1
		.amdhsa_float_round_mode_32 0
		.amdhsa_float_round_mode_16_64 0
		.amdhsa_float_denorm_mode_32 3
		.amdhsa_float_denorm_mode_16_64 3
		.amdhsa_dx10_clamp 1
		.amdhsa_ieee_mode 1
		.amdhsa_fp16_overflow 0
		.amdhsa_tg_split 0
		.amdhsa_exception_fp_ieee_invalid_op 0
		.amdhsa_exception_fp_denorm_src 0
		.amdhsa_exception_fp_ieee_div_zero 0
		.amdhsa_exception_fp_ieee_overflow 0
		.amdhsa_exception_fp_ieee_underflow 0
		.amdhsa_exception_fp_ieee_inexact 0
		.amdhsa_exception_int_div_zero 0
	.end_amdhsa_kernel

amdhsa.kernels:
  - .agpr_count:     0
    .args:
      - .offset:         0
        .size:           224
        .value_kind:     by_value
      - .offset:         224
        .size:           4
        .value_kind:     hidden_block_count_x
      - .offset:         228
        .size:           4
        .value_kind:     hidden_block_count_y
      - .offset:         232
        .size:           4
        .value_kind:     hidden_block_count_z
      - .offset:         236
        .size:           2
        .value_kind:     hidden_group_size_x
      - .offset:         238
        .size:           2
        .value_kind:     hidden_group_size_y
      - .offset:         240
        .size:           2
        .value_kind:     hidden_group_size_z
      - .offset:         242
        .size:           2
        .value_kind:     hidden_remainder_x
      - .offset:         244
        .size:           2
        .value_kind:     hidden_remainder_y
      - .offset:         246
        .size:           2
        .value_kind:     hidden_remainder_z
      - .offset:         264
        .size:           8
        .value_kind:     hidden_global_offset_x
      - .offset:         272
        .size:           8
        .value_kind:     hidden_global_offset_y
      - .offset:         280
        .size:           8
        .value_kind:     hidden_global_offset_z
      - .offset:         288
        .size:           2
        .value_kind:     hidden_grid_dims
      - .offset:         312
        .size:           8
        .value_kind:     hidden_multigrid_sync_arg
      - .offset:         344
        .size:           4
        .value_kind:     hidden_dynamic_lds_size
    .group_segment_fixed_size: 0
    .kernarg_segment_align: 8
    .kernarg_segment_size: 480
    .language:       OpenCL C
    .language_version:
      - 2
      - 0
    .max_flat_workgroup_size: 512
    .name:           _Z4mega6Params
    .private_segment_fixed_size: 0
    .sgpr_count:     106
    .sgpr_spill_count: 56
    .symbol:         _Z4mega6Params.kd
    .uniform_work_group_size: 1
    .uses_dynamic_stack: false
    .vgpr_count:     256
    .vgpr_spill_count: 0
    .wavefront_size: 64
